# e15 plus phase-0 adaLN item: the eight conditioning-vector loads of the silu LDS fill issued together with counted waits (were eight serialized round trips)
# baseline (speedup 1.0000x reference)
.LBB0_719:
	global_load_dword v74, v[2:3], off
	v_lshl_add_u64 v[2:3], v[2:3], 0, s[80:81]
	global_load_dword v75, v[2:3], off
	v_lshl_add_u64 v[2:3], v[2:3], 0, s[80:81]
	global_load_dword v76, v[2:3], off
	v_lshl_add_u64 v[2:3], v[2:3], 0, s[80:81]
	global_load_dword v77, v[2:3], off
	v_lshl_add_u64 v[2:3], v[2:3], 0, s[80:81]
	global_load_dword v78, v[2:3], off
	v_lshl_add_u64 v[2:3], v[2:3], 0, s[80:81]
	global_load_dword v79, v[2:3], off
	v_lshl_add_u64 v[2:3], v[2:3], 0, s[80:81]
	global_load_dword v80, v[2:3], off
	v_lshl_add_u64 v[2:3], v[2:3], 0, s[80:81]
	global_load_dword v81, v[2:3], off
	v_ashrrev_i32_e32 v6, 10, v4
	v_and_b32_e32 v7, 0xffc, v0
	v_lshlrev_b32_e32 v7, 2, v7
	v_lshlrev_b32_e32 v6, 2, v6
	v_add_u32_e32 v0, 0x800, v0
	v_add3_u32 v6, 0, v7, v6
	v_add_u32_e32 v4, 0x200, v4
	s_waitcnt vmcnt(7)
	v_mul_f32_e32 v9, 0xbfb8aa3b, v74
	v_exp_f32_e32 v9, v9
	s_nop 0
	v_add_f32_e32 v8, 1.0, v9
	v_rcp_f32_e32 v9, v8
	s_nop 0
	v_mul_f32_e32 v5, v74, v9
	ds_write_b32 v6, v5
	v_ashrrev_i32_e32 v6, 10, v4
	v_and_b32_e32 v7, 0xffc, v0
	v_lshlrev_b32_e32 v7, 2, v7
	v_lshlrev_b32_e32 v6, 2, v6
	v_add_u32_e32 v0, 0x800, v0
	v_add3_u32 v6, 0, v7, v6
	v_add_u32_e32 v4, 0x200, v4
	s_waitcnt vmcnt(6)
	v_mul_f32_e32 v9, 0xbfb8aa3b, v75
	v_exp_f32_e32 v9, v9
	s_nop 0
	v_add_f32_e32 v8, 1.0, v9
	v_rcp_f32_e32 v9, v8
	s_nop 0
	v_mul_f32_e32 v5, v75, v9
	ds_write_b32 v6, v5
	v_ashrrev_i32_e32 v6, 10, v4
	v_and_b32_e32 v7, 0xffc, v0
	v_lshlrev_b32_e32 v7, 2, v7
	v_lshlrev_b32_e32 v6, 2, v6
	v_add_u32_e32 v0, 0x800, v0
	v_add3_u32 v6, 0, v7, v6
	v_add_u32_e32 v4, 0x200, v4
	s_waitcnt vmcnt(5)
	v_mul_f32_e32 v9, 0xbfb8aa3b, v76
	v_exp_f32_e32 v9, v9
	s_nop 0
	v_add_f32_e32 v8, 1.0, v9
	v_rcp_f32_e32 v9, v8
	s_nop 0
	v_mul_f32_e32 v5, v76, v9
	ds_write_b32 v6, v5
	v_ashrrev_i32_e32 v6, 10, v4
	v_and_b32_e32 v7, 0xffc, v0
	v_lshlrev_b32_e32 v7, 2, v7
	v_lshlrev_b32_e32 v6, 2, v6
	v_add_u32_e32 v0, 0x800, v0
	v_add3_u32 v6, 0, v7, v6
	v_add_u32_e32 v4, 0x200, v4
	s_waitcnt vmcnt(4)
	v_mul_f32_e32 v9, 0xbfb8aa3b, v77
	v_exp_f32_e32 v9, v9
	s_nop 0
	v_add_f32_e32 v8, 1.0, v9
	v_rcp_f32_e32 v9, v8
	s_nop 0
	v_mul_f32_e32 v5, v77, v9
	ds_write_b32 v6, v5
	v_ashrrev_i32_e32 v6, 10, v4
	v_and_b32_e32 v7, 0xffc, v0
	v_lshlrev_b32_e32 v7, 2, v7
	v_lshlrev_b32_e32 v6, 2, v6
	v_add_u32_e32 v0, 0x800, v0
	v_add3_u32 v6, 0, v7, v6
	v_add_u32_e32 v4, 0x200, v4
	s_waitcnt vmcnt(3)
	v_mul_f32_e32 v9, 0xbfb8aa3b, v78
	v_exp_f32_e32 v9, v9
	s_nop 0
	v_add_f32_e32 v8, 1.0, v9
	v_rcp_f32_e32 v9, v8
	s_nop 0
	v_mul_f32_e32 v5, v78, v9
	ds_write_b32 v6, v5
	v_ashrrev_i32_e32 v6, 10, v4
	v_and_b32_e32 v7, 0xffc, v0
	v_lshlrev_b32_e32 v7, 2, v7
	v_lshlrev_b32_e32 v6, 2, v6
	v_add_u32_e32 v0, 0x800, v0
	v_add3_u32 v6, 0, v7, v6
	v_add_u32_e32 v4, 0x200, v4
	s_waitcnt vmcnt(2)
	v_mul_f32_e32 v9, 0xbfb8aa3b, v79
	v_exp_f32_e32 v9, v9
	s_nop 0
	v_add_f32_e32 v8, 1.0, v9
	v_rcp_f32_e32 v9, v8
	s_nop 0
	v_mul_f32_e32 v5, v79, v9
	ds_write_b32 v6, v5
	v_ashrrev_i32_e32 v6, 10, v4
	v_and_b32_e32 v7, 0xffc, v0
	v_lshlrev_b32_e32 v7, 2, v7
	v_lshlrev_b32_e32 v6, 2, v6
	v_add_u32_e32 v0, 0x800, v0
	v_add3_u32 v6, 0, v7, v6
	v_add_u32_e32 v4, 0x200, v4
	s_waitcnt vmcnt(1)
	v_mul_f32_e32 v9, 0xbfb8aa3b, v80
	v_exp_f32_e32 v9, v9
	s_nop 0
	v_add_f32_e32 v8, 1.0, v9
	v_rcp_f32_e32 v9, v8
	s_nop 0
	v_mul_f32_e32 v5, v80, v9
	ds_write_b32 v6, v5
	v_ashrrev_i32_e32 v6, 10, v4
	v_and_b32_e32 v7, 0xffc, v0
	v_lshlrev_b32_e32 v7, 2, v7
	v_lshlrev_b32_e32 v6, 2, v6
	v_add_u32_e32 v0, 0x800, v0
	v_add3_u32 v6, 0, v7, v6
	v_add_u32_e32 v4, 0x200, v4
	s_waitcnt vmcnt(0)
	v_mul_f32_e32 v9, 0xbfb8aa3b, v81
	v_exp_f32_e32 v9, v9
	s_nop 0
	v_add_f32_e32 v8, 1.0, v9
	v_rcp_f32_e32 v9, v8
	s_nop 0
	v_mul_f32_e32 v5, v81, v9
	ds_write_b32 v6, v5
